# row-wise residual phases: the Y operand (read exactly once) loaded with the nontemporal hint, like the residual stream
# speedup vs baseline: 1.0054x; 1.0023x over previous
; #define GAS __attribute__((address_space(1)))
; DI void rw_rows4(const RowIO4& R, const float* __restrict__ ga, const float* __restrict__ gb, int lane) {
;   f32x4 x[4][4]; u32x2 yr[4][4];
;   f32x4 ga4[4], gt4[4], gb4[4], sh4[4], sc4[4];
; #pragma unroll
;   for (int r = 0; r < 4; ++r)
; #pragma unroll
;     for (int i = 0; i < 4; ++i) x[r][i] = __builtin_nontemporal_load((const GAS f32x4*)(R.xin + r * 1024 + 4 * lane + 256 * i));
;   if (R.y) {
; #pragma unroll
;     for (int r = 0; r < 4; ++r)
; #pragma unroll
;       for (int i = 0; i < 4; ++i) yr[r][i] = *(const GAS u32x2*)(R.y + r * 1024 + 4 * lane + 256 * i);
; #pragma unroll
;     for (int i = 0; i < 4; ++i) { ga4[i] = *(const GAS f32x4*)(ga + 4 * lane + 256 * i); gt4[i] = *(const GAS f32x4*)(R.gate + 4 * lane + 256 * i); }
;   }
;   if (R.hout) {
; #pragma unroll
;     for (int i = 0; i < 4; ++i) { gb4[i] = *(const GAS f32x4*)(gb + 4 * lane + 256 * i); sh4[i] = *(const GAS f32x4*)(R.shift + 4 * lane + 256 * i); sc4[i] = *(const GAS f32x4*)(R.scale + 4 * lane + 256 * i); }
;   }
.LBB0_366:
	v_lshl_add_u64 v[18:19], s[18:19], 0, v[0:1]
	s_movk_i32 s11, 0x1000
	v_add_co_u32_e32 v20, vcc, s11, v18
	s_movk_i32 s10, 0x2000
	s_nop 0
	v_addc_co_u32_e32 v21, vcc, 0, v19, vcc
	v_add_co_u32_e32 v22, vcc, s10, v18
	s_movk_i32 s10, 0x3000
	s_nop 0
	v_addc_co_u32_e32 v23, vcc, 0, v19, vcc
	v_add_co_u32_e32 v18, vcc, s10, v18
	global_load_dwordx4 v[126:129], v0, s[18:19] nt
	global_load_dwordx4 v[122:125], v0, s[18:19] offset:1024 nt
	global_load_dwordx4 v[118:121], v0, s[18:19] offset:2048 nt
	global_load_dwordx4 v[114:117], v0, s[18:19] offset:3072 nt
	v_addc_co_u32_e32 v19, vcc, 0, v19, vcc
	global_load_dwordx4 v[106:109], v[20:21], off offset:1024 nt
	global_load_dwordx4 v[102:105], v[20:21], off offset:2048 nt
	global_load_dwordx4 v[110:113], v[22:23], off offset:-4096 nt
	global_load_dwordx4 v[94:97], v[22:23], off nt
	global_load_dwordx4 v[90:93], v[22:23], off offset:1024 nt
	global_load_dwordx4 v[86:89], v[22:23], off offset:2048 nt
	global_load_dwordx4 v[82:85], v[22:23], off offset:3072 nt
	global_load_dwordx4 v[98:101], v[20:21], off offset:3072 nt
	global_load_dwordx4 v[70:73], v[18:19], off nt
	global_load_dwordx4 v[62:65], v[18:19], off offset:1024 nt
	global_load_dwordx4 v[54:57], v[18:19], off offset:2048 nt
	global_load_dwordx4 v[50:53], v[18:19], off offset:3072 nt
	v_lshl_add_u64 v[18:19], s[28:29], 1, v[140:141]
	global_load_dwordx2 v[194:195], v[18:19], off nt
	global_load_dwordx2 v[196:197], v[18:19], off offset:512 nt
	global_load_dwordx2 v[168:169], v[18:19], off offset:1024 nt
	global_load_dwordx2 v[192:193], v[18:19], off offset:1536 nt
	global_load_dwordx2 v[182:183], v[18:19], off offset:2048 nt
	global_load_dwordx2 v[184:185], v[18:19], off offset:2560 nt
	global_load_dwordx2 v[178:179], v[18:19], off offset:3072 nt
	global_load_dwordx2 v[180:181], v[18:19], off offset:3584 nt
	v_add_co_u32_e32 v18, vcc, s11, v18
	s_add_u32 s40, s42, s62
	s_nop 0
	v_addc_co_u32_e32 v19, vcc, 0, v19, vcc
	s_addc_u32 s41, s43, 0
	global_load_dwordx2 v[174:175], v[18:19], off nt
	global_load_dwordx2 v[176:177], v[18:19], off offset:512 nt
	global_load_dwordx2 v[170:171], v[18:19], off offset:1024 nt
	global_load_dwordx2 v[172:173], v[18:19], off offset:1536 nt
	global_load_dwordx2 v[164:165], v[18:19], off offset:2048 nt
	global_load_dwordx2 v[166:167], v[18:19], off offset:2560 nt
	global_load_dwordx2 v[160:161], v[18:19], off offset:3072 nt
	global_load_dwordx2 v[162:163], v[18:19], off offset:3584 nt
	global_load_dwordx4 v[78:81], v0, s[40:41]
	global_load_dwordx4 v[74:77], v0, s[40:41] offset:1024
	global_load_dwordx4 v[66:69], v0, s[40:41] offset:2048
	global_load_dwordx4 v[58:61], v0, s[40:41] offset:3072
	s_cmp_lg_u64 s[46:47], 0
	s_movk_i32 s10, 0x1000
	s_cselect_b64 s[18:19], -1, 0
	s_cmp_eq_u64 s[46:47], 0
	s_cbranch_scc1 .LBB0_368
	global_load_dwordx4 v[144:147], v0, s[22:23]
	global_load_dwordx4 v[42:45], v[142:143], off
	global_load_dwordx4 v[30:33], v[142:143], off offset:1024
	global_load_dwordx4 v[46:49], v0, s[20:21]
	global_load_dwordx4 v[38:41], v0, s[20:21] offset:1024
	global_load_dwordx4 v[148:151], v0, s[22:23] offset:1024
	global_load_dwordx4 v[222:225], v0, s[22:23] offset:2048
	global_load_dwordx4 v[26:29], v[142:143], off offset:2048
	global_load_dwordx4 v[18:21], v[142:143], off offset:3072
	global_load_dwordx4 v[226:229], v0, s[22:23] offset:3072
	global_load_dwordx4 v[34:37], v0, s[20:21] offset:2048
	global_load_dwordx4 v[22:25], v0, s[20:21] offset:3072
	s_waitcnt vmcnt(0)
	v_pk_add_f32 v[158:159], v[146:147], 1.0 op_sel_hi:[1,0]
	v_pk_add_f32 v[156:157], v[144:145], 1.0 op_sel_hi:[1,0]
	v_pk_add_f32 v[154:155], v[150:151], 1.0 op_sel_hi:[1,0]
	v_pk_add_f32 v[152:153], v[148:149], 1.0 op_sel_hi:[1,0]
	v_pk_add_f32 v[150:151], v[224:225], 1.0 op_sel_hi:[1,0]
	v_pk_add_f32 v[148:149], v[222:223], 1.0 op_sel_hi:[1,0]
	v_pk_add_f32 v[146:147], v[228:229], 1.0 op_sel_hi:[1,0]
	v_pk_add_f32 v[144:145], v[226:227], 1.0 op_sel_hi:[1,0]
	s_branch .LBB0_369
